# S5: carry scan fused into the state-GEMM phase (each workgroup scans the (group, 2 batches) of its own state tile), the state->scan grid barrier becomes a workgroup-local sync
# baseline (speedup 1.0000x reference)
.LBB0_252:
	s_mov_b64 s[6:7], s[84:85]
	s_mov_b32 s3, s72
	v_mbcnt_lo_u32_b32 v0, -1, 0
	v_mbcnt_hi_u32_b32 v0, -1, v0
	s_getreg_b32 s2, hwreg(HW_REG_HW_ID, 0, 6)
	s_lshl_b32 s2, s2, 2
	s_and_b32 s2, s2, 0xfc
	s_add_i32 s2, s2, 0
	s_add_i32 s2, s2, 0x23400
	v_mov_b32_e32 v2, s2
	ds_read_b32 v2, v2
	s_waitcnt vmcnt(0) lgkmcnt(0)
	v_sub_u32_e32 v0, 0, v0
	s_waitcnt vmcnt(0) lgkmcnt(0)
	s_barrier
	v_readfirstlane_b32 s2, v2
	s_lshl_b32 s2, s2, 6
	s_nop 0
	v_cmp_eq_u32_e32 vcc, s2, v0
	s_mov_b64 s[4:5], exec
	buffer_inv sc1
	s_waitcnt vmcnt(0)
	s_branch .LBB0_320
	v_mov_b32_e32 v0, s86
	s_load_dwordx2 s[6:7], s[6:7], 0x110
	s_getreg_b32 s2, hwreg(HW_REG_XCC_ID, 0, 4)
	ds_read_b32 v3, v0
	v_mov_b32_e32 v0, s87
	ds_read_b32 v2, v0
	s_and_b32 s2, s2, 15
	s_waitcnt lgkmcnt(0)
	v_cmp_ne_u32_e32 vcc, 0, v3
	s_cbranch_vccnz .LBB0_262
	s_add_u32 s8, s6, 0x4400
	s_addc_u32 s9, s7, 0
	s_add_u32 s10, s6, 0x4500
	s_addc_u32 s11, s7, 0
	s_add_u32 s12, s6, 0x4600
	s_addc_u32 s13, s7, 0
	s_add_u32 s14, s6, 0x4700
	s_addc_u32 s15, s7, 0
	s_add_u32 s16, s6, 0x4800
	s_addc_u32 s17, s7, 0
	s_add_u32 s18, s6, 0x4900
	s_addc_u32 s19, s7, 0
	s_add_u32 s20, s6, 0x4a00
	s_addc_u32 s21, s7, 0
	s_add_u32 s22, s6, 0x4b00
	s_addc_u32 s23, s7, 0
	s_add_u32 s24, s6, 0x4c00
	s_addc_u32 s25, s7, 0
	s_add_u32 s26, s6, 0x4d00
	s_addc_u32 s27, s7, 0
	s_add_u32 s28, s6, 0x4e00
	s_addc_u32 s29, s7, 0
	s_add_u32 s30, s6, 0x4f00
	s_addc_u32 s31, s7, 0
	s_add_u32 s34, s6, 0x5000
	s_addc_u32 s35, s7, 0
	s_add_u32 s36, s6, 0x5100
	s_addc_u32 s37, s7, 0
	s_add_u32 s38, s6, 0x5200
	s_addc_u32 s39, s7, 0
	s_add_u32 s40, s6, 0x5300
	s_addc_u32 s41, s7, 0
	s_mov_b32 s45, 0x400000
	s_branch .LBB0_257

.LBB0_320:
	s_or_b64 exec, exec, s[4:5]
	s_mov_b64 s[12:13], s[84:85]
	s_waitcnt lgkmcnt(0)
	s_barrier
	v_mbcnt_lo_u32_b32 v0, -1, 0
	v_mbcnt_hi_u32_b32 v0, -1, v0
	s_getreg_b32 s2, hwreg(HW_REG_HW_ID, 0, 6)
	s_lshl_b32 s2, s2, 2
	s_and_b32 s2, s2, 0xfc
	s_add_i32 s2, s2, 0
	s_add_i32 s2, s2, 0x23400
	v_mov_b32_e32 v2, s2
	ds_read_b32 v2, v2
	v_readlane_b32 s3, v255, 2
	s_waitcnt lgkmcnt(0)
	v_readfirstlane_b32 s2, v2
	v_readlane_b32 s100, v255, 10
	s_nop 0
	s_and_b32 s101, s100, 3
	s_lshl_b32 s101, s101, 1
	s_add_i32 s101, s101, s2
	s_lshl_b32 s101, s101, 12
	s_lshr_b32 s100, s100, 2
	s_lshl_b32 s100, s100, 6
	s_or_b32 s101, s101, s100
	s_cmp_lt_u32 s2, 2
	s_cselect_b32 s101, s101, 0x8000
	v_add_u32_e32 v3, s101, v0
	s_mov_b32 s2, 0x8000
	v_cmp_gt_i32_e32 vcc, s2, v3
	s_and_saveexec_b64 s[10:11], vcc
	s_cbranch_execz .LBB0_326
	s_load_dwordx2 s[2:3], s[12:13], 0xc8
	s_load_dwordx4 s[4:7], s[12:13], 0xb8
	v_bfe_u32 v4, v3, 6, 6
	v_readlane_b32 s8, v255, 17
	v_and_b32_e32 v2, 63, v0
	v_readlane_b32 s9, v255, 18
	v_or_b32_e32 v0, s8, v4
	s_waitcnt lgkmcnt(0)
	v_lshl_add_u64 v[6:7], v[0:1], 2, s[2:3]
	global_load_dword v5, v[6:7], off
	v_lshlrev_b64 v[6:7], 8, v[0:1]
	v_lshl_or_b32 v6, v2, 2, v6
	v_lshl_add_u64 v[8:9], s[6:7], 0, v[6:7]
	global_load_dword v0, v[8:9], off
	v_lshl_add_u64 v[6:7], s[4:5], 0, v[6:7]
	global_load_dword v7, v[6:7], off
	s_waitcnt vmcnt(2)
	v_mul_f32_e32 v5, 0x3fb8aa3b, v5
	v_exp_f32_e32 v8, v5
	s_waitcnt vmcnt(1)
	v_mul_f32_e32 v0, 0x42000000, v0
	v_mul_f32_e32 v5, v8, v0
	v_and_b32_e32 v6, 0x7fffffff, v5
	v_cmp_nlt_f32_e64 s[2:3], |v5|, s88
	s_and_saveexec_b64 s[4:5], s[2:3]
	s_xor_b64 s[14:15], exec, s[4:5]
	s_cbranch_execz .LBB0_323
	v_lshrrev_b32_e32 v0, 23, v6
	v_add_u32_e32 v0, 0xffffff88, v0
	v_cmp_lt_u32_e32 vcc, 63, v0
	s_nop 1
	v_cndmask_b32_e32 v9, 0, v227, vcc
	v_add_u32_e32 v0, v9, v0
	v_cmp_lt_u32_e64 s[4:5], 31, v0
	s_nop 1
	v_cndmask_b32_e64 v9, 0, v228, s[4:5]
	v_add_u32_e32 v0, v9, v0
	v_cmp_lt_u32_e64 s[6:7], 31, v0
	s_nop 1
	v_cndmask_b32_e64 v9, 0, v228, s[6:7]
	v_add_u32_e32 v9, v9, v0
	v_and_b32_e32 v0, 0x7fffff, v6
	v_or_b32_e32 v22, 0x800000, v0
	v_mad_u64_u32 v[10:11], s[2:3], v22, s89, 0
	v_mov_b32_e32 v0, v11
	v_mad_u64_u32 v[12:13], s[2:3], v22, s90, v[0:1]
	v_mov_b32_e32 v0, v13
	v_mad_u64_u32 v[14:15], s[2:3], v22, s91, v[0:1]
	v_mov_b32_e32 v0, v15
	v_mad_u64_u32 v[16:17], s[2:3], v22, s92, v[0:1]
	v_mov_b32_e32 v0, v17
	v_mad_u64_u32 v[18:19], s[2:3], v22, s93, v[0:1]
	v_mov_b32_e32 v0, v19
	v_mad_u64_u32 v[20:21], s[2:3], v22, s94, v[0:1]
	v_mov_b32_e32 v0, v21
	v_mad_u64_u32 v[22:23], s[2:3], v22, s95, v[0:1]
	v_cndmask_b32_e32 v11, v20, v16, vcc
	v_cndmask_b32_e32 v0, v22, v18, vcc
	v_cndmask_b32_e32 v15, v23, v20, vcc
	v_cndmask_b32_e64 v13, v0, v11, s[4:5]
	v_cndmask_b32_e64 v0, v15, v0, s[4:5]
	v_cndmask_b32_e32 v15, v18, v14, vcc
	v_cndmask_b32_e64 v11, v11, v15, s[4:5]
	v_cndmask_b32_e64 v0, v0, v13, s[6:7]
	v_cndmask_b32_e64 v13, v13, v11, s[6:7]
	v_sub_u32_e32 v17, 32, v9
	v_alignbit_b32 v18, v0, v13, v17
	v_cmp_eq_u32_e64 s[8:9], 0, v9
	v_cndmask_b32_e32 v10, v14, v10, vcc
	s_nop 0
	v_cndmask_b32_e64 v9, v18, v0, s[8:9]
	v_cndmask_b32_e32 v0, v16, v12, vcc
	v_cndmask_b32_e64 v12, v15, v0, s[4:5]
	v_cndmask_b32_e64 v11, v11, v12, s[6:7]
	v_alignbit_b32 v15, v13, v11, v17
	v_cndmask_b32_e64 v13, v15, v13, s[8:9]
	v_bfe_u32 v18, v9, 29, 1
	v_cndmask_b32_e64 v0, v0, v10, s[4:5]
	v_alignbit_b32 v15, v9, v13, 30
	v_sub_u32_e32 v19, 0, v18
	v_cndmask_b32_e64 v0, v12, v0, s[6:7]
	v_xor_b32_e32 v15, v15, v19
	v_alignbit_b32 v10, v11, v0, v17
	v_cndmask_b32_e64 v10, v10, v11, s[8:9]
	v_ffbh_u32_e32 v12, v15
	v_alignbit_b32 v11, v13, v10, 30
	v_min_u32_e32 v12, 32, v12
	v_alignbit_b32 v0, v10, v0, 30
	v_xor_b32_e32 v11, v11, v19
	v_sub_u32_e32 v13, 31, v12
	v_xor_b32_e32 v0, v0, v19
	v_alignbit_b32 v14, v15, v11, v13
	v_alignbit_b32 v0, v11, v0, v13
	v_alignbit_b32 v10, v14, v0, 9
	v_ffbh_u32_e32 v11, v10
	v_min_u32_e32 v11, 32, v11
	v_lshrrev_b32_e32 v16, 29, v9
	v_not_b32_e32 v13, v11
	v_alignbit_b32 v0, v10, v0, v13
	v_lshlrev_b32_e32 v10, 31, v16
	v_or_b32_e32 v13, 0x33000000, v10
	v_add_lshl_u32 v11, v11, v12, 23
	v_lshrrev_b32_e32 v0, 9, v0
	v_sub_u32_e32 v11, v13, v11
	v_or_b32_e32 v10, 0.5, v10
	v_lshlrev_b32_e32 v12, 23, v12
	v_or_b32_e32 v0, v11, v0
	v_lshrrev_b32_e32 v11, 9, v14
	v_sub_u32_e32 v10, v10, v12
	v_or_b32_e32 v10, v11, v10
	v_mul_f32_e32 v11, 0x3fc90fda, v10
	v_fma_f32 v12, v10, s96, -v11
	v_fmac_f32_e32 v12, 0x33a22168, v10
	v_fmac_f32_e32 v12, 0x3fc90fda, v0
	v_lshrrev_b32_e32 v9, 30, v9
	v_add_f32_e32 v0, v11, v12
	v_add_u32_e32 v9, v18, v9
